# retention scan loop: row-index/address math strength-reduced (uniform direction steps in SGPRs, loop-invariant lane part, SGPR-base + 32-bit offset prefetch loads): 24 fewer VALU ops per iteration
# baseline (speedup 1.0000x reference)
.LBB0_1368:
	s_cmp_lt_i32 s14, 0
	s_cselect_b64 s[4:5], -1, 0
	s_and_b64 vcc, exec, s[4:5]
	s_cbranch_vccnz .LBB0_1355
	v_sub_co_u32_e64 v0, s[36:37], s14, 64
	s_xor_b64 s[6:7], s[36:37], -1
	s_and_b64 s[0:1], s[36:37], exec
	v_readfirstlane_b32 s0, v0
	s_cselect_b32 s18, s14, s0
	s_cselect_b32 s55, s48, 0x100
	s_ashr_i32 s14, s18, 4
	s_lshl_b32 s15, s14, 10
	s_bfe_u32 s1, s18, 0x30001
	s_and_b32 s0, s18, 1
	s_add_i32 s38, s15, 0x2000
	s_lshl_b32 s39, s14, 8
	s_and_b64 s[14:15], s[36:37], exec
	s_cselect_b32 s56, s38, s39
	s_lshl_b32 s15, s0, 3
	s_and_b32 s14, s18, -16
	s_or_b32 s18, s15, s1
	s_or_b32 s14, s18, s14
	s_ashr_i32 s15, s14, 31
	s_lshl_b64 s[14:15], s[14:15], 16
	s_add_u32 s38, s44, s14
	s_addc_u32 s39, s45, s15
	s_and_b64 s[36:37], s[36:37], exec
	s_cselect_b32 s43, s39, 0
	s_cselect_b32 s42, s38, 0
	s_lshl_b32 s18, s18, 2
	v_readlane_b32 s76, v254, 0
	v_mov_b32_e32 v0, s18
	v_readlane_b32 s78, v254, 2
	v_readlane_b32 s79, v254, 3
	v_mov_b32_e32 v1, v224
	v_mov_b32_e32 v127, v2
	v_mov_b32_e32 v125, v2
	v_mov_b32_e32 v123, v2
	v_mov_b32_e32 v119, v2
	global_load_dword v4, v0, s[78:79]
	v_mov_b32_e32 v117, v2
	v_bfe_u32 v3, v1, 4, 2
	v_lshlrev_b32_e32 v49, 2, v3
	s_waitcnt vmcnt(4)
	v_or_b32_e32 v9, 3, v49
	v_lshlrev_b32_e32 v10, 8, v9
	v_and_b32_e32 v10, 0xe00, v10
	v_or_b32_e32 v82, 0x4000, v10
	v_ashrrev_i32_e32 v174, 4, v1
	s_waitcnt vmcnt(3)
	v_ashrrev_i32_e32 v5, 2, v1
	v_lshlrev_b32_e32 v6, 6, v1
	v_sub_u32_e32 v7, s55, v174
	v_and_b32_e32 v0, -16, v5
	v_bfi_b32 v112, -16, v5, v1
	v_and_b32_e32 v5, 0xc00, v6
	v_add_u32_e32 v6, 32, v174
	v_subrev_u32_e32 v7, 33, v7
	v_and_b32_e32 v173, 15, v1
	v_or_b32_e32 v102, 0x7000, v5
	v_or_b32_e32 v104, 0x3200, v5
	v_or_b32_e32 v106, 0x7200, v5
	v_or_b32_e32 v116, 0xf000, v5
	v_or_b32_e32 v114, 0xb200, v5
	v_or_b32_e32 v140, 0xf200, v5
	v_or_b32_e32 v8, 2, v49
	v_lshlrev_b32_e32 v80, 8, v8
	v_lshlrev_b32_e32 v76, 10, v3
	v_ashrrev_i32_e32 v113, 31, v112
	v_or_b32_e32 v126, 0xa000, v76
	v_or_b32_e32 v124, 0xe000, v76
	v_or_b32_e32 v122, 0xa200, v76
	v_or_b32_e32 v118, 0xb000, v76
	v_mov_b32_e32 v115, v2
	v_mov_b32_e32 v141, v2
	v_mov_b32_e32 v109, v2
	v_mov_b32_e32 v111, v2
	v_or_b32_e32 v108, 0x8000, v76
	v_or_b32_e32 v110, 0xc000, v76
	v_or_b32_e32 v138, 0x8200, v76
	v_mov_b32_e32 v139, v2
	v_or_b32_e32 v134, 0x9000, v76
	v_mov_b32_e32 v135, v2
	v_or_b32_e32 v132, 0xd000, v76
	v_mov_b32_e32 v133, v2
	v_or_b32_e32 v130, 0x9200, v76
	v_mov_b32_e32 v131, v2
	v_or_b32_e32 v128, 0xd200, v76
	v_mov_b32_e32 v129, v2
	v_or_b32_e32 v120, 0xe200, v76
	v_mov_b32_e32 v121, v2
	v_mov_b32_e32 v93, v2
	v_mov_b32_e32 v95, v2
	v_mov_b32_e32 v97, v2
	v_mov_b32_e32 v101, v2
	v_mov_b32_e32 v103, v2
	v_mov_b32_e32 v105, v2
	v_mov_b32_e32 v107, v2
	v_or_b32_e32 v92, 0x2000, v76
	v_or_b32_e32 v94, 0x6000, v76
	v_or_b32_e32 v96, 0x2200, v76
	v_or_b32_e32 v100, 0x3000, v76
	v_or_b32_e32 v136, 0xc200, v76
	v_mov_b32_e32 v137, v2
	v_mov_b32_e32 v77, v2
	v_mov_b32_e32 v79, v2
	v_mov_b32_e32 v81, v2
	v_mov_b32_e32 v83, v2
	v_mov_b32_e32 v85, v2
	v_mov_b32_e32 v87, v2
	v_mov_b32_e32 v89, v2
	v_mov_b32_e32 v91, v2
	v_mov_b32_e32 v99, v2
	v_or_b32_e32 v78, 0x4000, v76
	v_or_b32_e32 v84, 0x1000, v76
	v_or_b32_e32 v86, 0x5000, v76
	v_or_b32_e32 v88, 0x1200, v76
	v_or_b32_e32 v90, 0x5200, v76
	v_or_b32_e32 v98, 0x6200, v76
	v_xor_b32_e32 v23, 28, v49
	s_waitcnt vmcnt(0)
	v_mul_f32_e64 v11, |v4|, s49
	v_exp_f32_e32 v11, v11
	v_max_f32_e32 v4, v4, v4
	v_min_f32_e32 v4, 0, v4
	v_lshlrev_b32_e32 v48, 3, v1
	v_add_f32_e32 v10, 1.0, v11
	v_cmp_gt_f32_e32 vcc, s50, v10
	s_and_b64 s[36:37], vcc, exec
	s_cselect_b32 s18, 32, 0
	s_lshl_b32 s46, s1, 8
	s_add_u32 s36, s60, s46
	v_ldexp_f32 v10, v10, s18
	s_addc_u32 s37, s61, 0
	v_log_f32_e32 v10, v10
	s_add_u32 s38, s17, s46
	s_addc_u32 s39, s19, 0
	s_add_u32 s40, s88, s46
	s_addc_u32 s41, s89, 0
	v_mul_f32_e32 v12, 0x3f317217, v10
	s_cmp_eq_u32 s0, 0
	v_cndmask_b32_e32 v11, 0, v172, vcc
	v_fma_f32 v12, v10, s51, -v12
	s_cselect_b64 vcc, -1, 0
	v_fmac_f32_e32 v12, 0x3377d1cf, v10
	s_and_b64 s[0:1], vcc, exec
	v_fmac_f32_e32 v12, 0x3f317217, v10
	v_cmp_lt_f32_e64 s[0:1], |v10|, s52
	v_cndmask_b32_e32 v22, v7, v6, vcc
	v_sub_u32_e32 v7, v173, v9
	v_cndmask_b32_e64 v6, v10, v12, s[0:1]
	v_sub_f32_e32 v6, v6, v11
	v_sub_f32_e32 v51, v4, v6
	v_sub_u32_e32 v4, v173, v49
	v_cvt_f32_u32_e32 v6, v4
	s_cselect_b32 s0, s53, 0xd522000
	s_add_u32 s0, s24, s0
	s_addc_u32 s1, s25, 0
	v_mul_f32_e32 v5, v51, v6
	v_add_u32_e32 v6, 16, v4
	v_cvt_f32_u32_e32 v6, v6
	v_mul_f32_e32 v5, 0x3fb8aa3b, v5
	s_add_u32 s46, s0, s46
	v_exp_f32_e32 v5, v5
	v_mul_f32_e32 v6, v51, v6
	s_addc_u32 s47, s1, 0
	v_cmp_lt_i32_e64 s[0:1], -1, v4
	v_xad_u32 v4, v49, -1, v173
	v_mul_f32_e32 v6, 0x3fb8aa3b, v6
	v_exp_f32_e32 v144, v6
	v_add_u32_e32 v6, 16, v4
	v_cvt_f32_u32_e32 v6, v6
	v_cndmask_b32_e64 v142, 0, v5, s[0:1]
	v_cvt_f32_u32_e32 v5, v4
	v_cmp_lt_i32_e64 s[0:1], -1, v4
	v_mul_f32_e32 v6, v51, v6
	v_sub_u32_e32 v4, v173, v8
	v_mul_f32_e32 v5, v51, v5
	v_mul_f32_e32 v6, 0x3fb8aa3b, v6
	v_mul_f32_e32 v5, 0x3fb8aa3b, v5
	v_exp_f32_e32 v145, v6
	v_add_u32_e32 v6, 16, v4
	v_exp_f32_e32 v5, v5
	v_cvt_f32_u32_e32 v6, v6
	v_cvt_f32_u32_e32 v8, v7
	s_lshr_b32 s58, s55, 5
	v_cndmask_b32_e64 v143, 0, v5, s[0:1]
	v_cvt_f32_u32_e32 v5, v4
	v_cmp_lt_i32_e64 s[0:1], -1, v4
	v_mul_f32_e32 v4, v51, v6
	v_add_u32_e32 v6, 16, v7
	v_cvt_f32_u32_e32 v6, v6
	v_mul_f32_e32 v5, v51, v5
	v_mul_f32_e32 v4, 0x3fb8aa3b, v4
	v_mul_f32_e32 v5, 0x3fb8aa3b, v5
	v_exp_f32_e32 v148, v4
	v_mul_f32_e32 v4, v51, v6
	v_exp_f32_e32 v5, v5
	v_mul_f32_e32 v4, 0x3fb8aa3b, v4
	v_exp_f32_e32 v149, v4
	v_xor_b32_e32 v4, 31, v49
	v_cvt_f32_ubyte0_e32 v4, v4
	v_mul_f32_e32 v4, v51, v4
	v_cndmask_b32_e64 v146, 0, v5, s[0:1]
	v_mul_f32_e32 v5, v51, v8
	v_mul_f32_e32 v4, 0x3fb8aa3b, v4
	v_mul_f32_e32 v5, 0x3fb8aa3b, v5
	v_exp_f32_e32 v150, v4
	v_xor_b32_e32 v4, 30, v49
	v_exp_f32_e32 v5, v5
	v_cvt_f32_ubyte0_e32 v4, v4
	v_mul_f32_e32 v4, v51, v4
	v_mul_f32_e32 v4, 0x3fb8aa3b, v4
	v_cmp_lt_i32_e64 s[0:1], -1, v7
	v_exp_f32_e32 v151, v4
	v_xor_b32_e32 v4, 29, v49
	s_cmp_eq_u64 s[42:43], 0
	v_cndmask_b32_e64 v147, 0, v5, s[0:1]
	v_cvt_f32_ubyte0_e32 v4, v4
	s_cselect_b64 s[0:1], -1, 0
	v_mul_f32_e32 v4, v51, v4
	s_and_b64 s[62:63], s[0:1], exec
	v_mul_f32_e32 v4, 0x3fb8aa3b, v4
	s_cselect_b32 s18, s45, s43
	s_cselect_b32 s42, s44, s42
	v_exp_f32_e32 v152, v4
	v_mov_b32_e32 v4, s42
	v_mov_b32_e32 v5, s18
	v_lshl_add_u64 v[4:5], v[112:113], 2, v[4:5]
	v_lshl_add_u64 v[6:7], v[4:5], 0, v[118:119]
	v_lshl_add_u64 v[8:9], v[4:5], 0, v[116:117]
	v_lshl_add_u64 v[10:11], v[4:5], 0, v[114:115]
	v_lshl_add_u64 v[12:13], v[4:5], 0, v[140:141]
	v_lshl_add_u64 v[14:15], v[4:5], 0, v[126:127]
	v_lshl_add_u64 v[16:17], v[4:5], 0, v[124:125]
	v_lshl_add_u64 v[18:19], v[4:5], 0, v[122:123]
	v_lshl_add_u64 v[20:21], v[4:5], 0, v[120:121]
	global_load_dword v24, v[6:7], off
	global_load_dword v25, v[8:9], off
	global_load_dword v26, v[10:11], off
	global_load_dword v27, v[12:13], off
	global_load_dword v28, v[14:15], off
	global_load_dword v29, v[16:17], off
	global_load_dword v30, v[18:19], off
	global_load_dword v31, v[20:21], off
	v_lshl_add_u64 v[6:7], v[4:5], 0, v[134:135]
	v_lshl_add_u64 v[8:9], v[4:5], 0, v[132:133]
	v_lshl_add_u64 v[10:11], v[4:5], 0, v[130:131]
	v_lshl_add_u64 v[12:13], v[4:5], 0, v[128:129]
	v_lshl_add_u64 v[14:15], v[4:5], 0, v[108:109]
	v_lshl_add_u64 v[16:17], v[4:5], 0, v[110:111]
	v_lshl_add_u64 v[18:19], v[4:5], 0, v[138:139]
	v_lshl_add_u64 v[20:21], v[4:5], 0, v[136:137]
	global_load_dword v32, v[6:7], off
	global_load_dword v33, v[8:9], off
	global_load_dword v34, v[10:11], off
	global_load_dword v35, v[12:13], off
	global_load_dword v36, v[14:15], off
	global_load_dword v37, v[16:17], off
	global_load_dword v38, v[18:19], off
	global_load_dword v39, v[20:21], off
	v_lshl_add_u64 v[6:7], v[4:5], 0, v[100:101]
	v_lshl_add_u64 v[8:9], v[4:5], 0, v[102:103]
	v_lshl_add_u64 v[10:11], v[4:5], 0, v[104:105]
	v_lshl_add_u64 v[12:13], v[4:5], 0, v[106:107]
	v_lshl_add_u64 v[14:15], v[4:5], 0, v[92:93]
	v_lshl_add_u64 v[16:17], v[4:5], 0, v[94:95]
	v_lshl_add_u64 v[18:19], v[4:5], 0, v[96:97]
	v_lshl_add_u64 v[20:21], v[4:5], 0, v[98:99]
	global_load_dword v40, v[6:7], off
	global_load_dword v41, v[8:9], off
	global_load_dword v42, v[10:11], off
	global_load_dword v43, v[12:13], off
	global_load_dword v44, v[14:15], off
	global_load_dword v45, v[16:17], off
	global_load_dword v46, v[18:19], off
	global_load_dword v47, v[20:21], off
	v_lshl_add_u64 v[6:7], v[4:5], 0, v[84:85]
	v_lshl_add_u64 v[8:9], v[4:5], 0, v[86:87]
	v_lshl_add_u64 v[10:11], v[4:5], 0, v[88:89]
	v_lshl_add_u64 v[12:13], v[4:5], 0, v[90:91]
	v_lshl_add_u64 v[14:15], v[4:5], 0, v[76:77]
	v_lshl_add_u64 v[16:17], v[4:5], 0, v[78:79]
	v_lshl_add_u64 v[18:19], v[4:5], 0, v[80:81]
	v_lshl_add_u64 v[4:5], v[4:5], 0, v[82:83]
	global_load_dword v52, v[6:7], off
	global_load_dword v53, v[8:9], off
	global_load_dword v54, v[10:11], off
	global_load_dword v55, v[12:13], off
	global_load_dword v56, v[14:15], off
	global_load_dword v57, v[16:17], off
	global_load_dword v58, v[18:19], off
	global_load_dword v59, v[4:5], off
	v_cvt_f32_ubyte0_e32 v4, v23
	v_mul_f32_e32 v4, v51, v4
	v_mul_f32_e32 v4, 0x3fb8aa3b, v4
	v_exp_f32_e32 v153, v4
	v_xor_b32_e32 v4, 15, v49
	v_cvt_f32_ubyte0_e32 v4, v4
	v_mul_f32_e32 v4, v51, v4
	v_mul_f32_e32 v4, 0x3fb8aa3b, v4
	v_exp_f32_e32 v154, v4
	v_xor_b32_e32 v4, 14, v49
	v_cvt_f32_ubyte0_e32 v4, v4
	v_mul_f32_e32 v4, v51, v4
	v_mul_f32_e32 v4, 0x3fb8aa3b, v4
	v_exp_f32_e32 v155, v4
	v_xor_b32_e32 v4, 13, v49
	v_cvt_f32_ubyte0_e32 v4, v4
	v_mul_f32_e32 v4, v51, v4
	v_xad_u32 v14, v174, -1, s55
	v_mul_f32_e32 v4, 0x3fb8aa3b, v4
	v_cndmask_b32_e32 v14, v14, v174, vcc
	v_exp_f32_e32 v156, v4
	v_add_u32_e32 v4, s56, v22
	v_add_u32_e32 v14, s56, v14
	v_and_b32_e32 v50, 0x78, v48
	v_ashrrev_i32_e32 v5, 31, v4
	v_ashrrev_i32_e32 v15, 31, v14
	v_lshlrev_b32_e32 v60, 1, v50
	v_lshlrev_b64 v[12:13], 13, v[4:5]
	v_lshlrev_b64 v[16:17], 13, v[14:15]
	v_or_b32_e32 v12, v12, v60
	v_or_b32_e32 v16, v16, v60
	v_lshl_add_u64 v[4:5], s[40:41], 0, v[12:13]
	v_lshl_add_u64 v[8:9], s[38:39], 0, v[12:13]
	v_lshl_add_u64 v[12:13], s[36:37], 0, v[12:13]
	v_lshl_add_u64 v[18:19], s[40:41], 0, v[16:17]
	global_load_dwordx4 v[4:7], v[4:5], off
	s_nop 0
	global_load_dwordx4 v[8:11], v[8:9], off
	s_nop 0
	global_load_dwordx4 v[12:15], v[12:13], off
	s_nop 0
	global_load_dwordx4 v[64:67], v[18:19], off
	v_lshl_add_u64 v[18:19], s[38:39], 0, v[16:17]
	v_lshl_add_u64 v[16:17], s[36:37], 0, v[16:17]
	global_load_dwordx4 v[68:71], v[18:19], off
	global_load_dwordx4 v[72:75], v[16:17], off
	v_xor_b32_e32 v16, 12, v49
	v_cvt_f32_ubyte0_e32 v16, v16
	v_mul_f32_e32 v16, v51, v16
	v_mul_f32_e32 v16, 0x3fb8aa3b, v16
	v_exp_f32_e32 v157, v16
	s_waitcnt vmcnt(37)
	v_cndmask_b32_e64 v16, v24, 0, s[0:1]
	v_bfe_u32 v1, v1, 2, 2
	v_or_b32_e32 v1, v49, v1
	v_mul_u32_u24_e32 v1, 0x88, v1
	v_lshlrev_b32_e32 v49, 1, v1
	v_and_b32_e32 v48, 24, v48
	v_ashrrev_i32_e32 v1, 31, v0
	v_add3_u32 v176, 0, v49, v48
	v_lshlrev_b32_e32 v48, 3, v3
	s_waitcnt vmcnt(29)
	v_cndmask_b32_e64 v24, v32, 0, s[0:1]
	v_mul_u32_u24_e32 v3, 0x88, v173
	v_lshl_add_u32 v177, v0, 1, v176
	v_lshlrev_b32_e32 v3, 1, v3
	v_lshl_add_u64 v[0:1], v[0:1], 1, s[46:47]
	v_mov_b32_e32 v49, v2
	s_mov_b32 s57, 3
	v_cndmask_b32_e64 v17, v25, 0, s[0:1]
	v_cndmask_b32_e64 v18, v26, 0, s[0:1]
	s_waitcnt vmcnt(21)
	v_cndmask_b32_e64 v32, v40, 0, s[0:1]
	v_cndmask_b32_e64 v19, v27, 0, s[0:1]
	v_cndmask_b32_e64 v20, v28, 0, s[0:1]
	v_cndmask_b32_e64 v21, v29, 0, s[0:1]
	v_cndmask_b32_e64 v22, v30, 0, s[0:1]
	v_cndmask_b32_e64 v23, v31, 0, s[0:1]
	v_cndmask_b32_e64 v25, v33, 0, s[0:1]
	v_cndmask_b32_e64 v26, v34, 0, s[0:1]
	v_cndmask_b32_e64 v27, v35, 0, s[0:1]
	s_waitcnt vmcnt(13)
	v_cndmask_b32_e64 v40, v52, 0, s[0:1]
	v_mul_f32_e32 v52, 0x42000000, v51
	v_mul_f32_e32 v52, 0x3fb8aa3b, v52
	v_exp_f32_e32 v158, v52
	v_add_u32_e32 v52, 17, v173
	v_cvt_f32_ubyte0_e32 v52, v52
	v_mul_f32_e32 v52, v51, v52
	v_mul_f32_e32 v52, 0x3fb8aa3b, v52
	v_exp_f32_e32 v160, v52
	v_add_u32_e32 v52, 1, v173
	v_cvt_f32_ubyte0_e32 v52, v52
	v_mul_f32_e32 v51, v51, v52
	v_mul_f32_e32 v51, 0x3fb8aa3b, v51
	v_exp_f32_e32 v162, v51
	v_mul_lo_u32 v51, v174, s54
	v_cndmask_b32_e64 v28, v36, 0, s[0:1]
	v_cndmask_b32_e64 v29, v37, 0, s[0:1]
	v_cndmask_b32_e64 v30, v38, 0, s[0:1]
	v_cndmask_b32_e64 v31, v39, 0, s[0:1]
	v_cndmask_b32_e64 v33, v41, 0, s[0:1]
	v_cndmask_b32_e64 v34, v42, 0, s[0:1]
	v_cndmask_b32_e64 v35, v43, 0, s[0:1]
	v_cndmask_b32_e64 v36, v44, 0, s[0:1]
	v_cndmask_b32_e64 v37, v45, 0, s[0:1]
	v_cndmask_b32_e64 v38, v46, 0, s[0:1]
	v_cndmask_b32_e64 v39, v47, 0, s[0:1]
	s_waitcnt vmcnt(12)
	v_cndmask_b32_e64 v41, v53, 0, s[0:1]
	s_waitcnt vmcnt(11)
	v_cndmask_b32_e64 v42, v54, 0, s[0:1]
	s_waitcnt vmcnt(10)
	v_cndmask_b32_e64 v43, v55, 0, s[0:1]
	s_waitcnt vmcnt(9)
	v_cndmask_b32_e64 v44, v56, 0, s[0:1]
	s_waitcnt vmcnt(8)
	v_cndmask_b32_e64 v45, v57, 0, s[0:1]
	s_waitcnt vmcnt(7)
	v_cndmask_b32_e64 v46, v58, 0, s[0:1]
	s_waitcnt vmcnt(6)
	v_cndmask_b32_e64 v47, v59, 0, s[0:1]
	v_add3_u32 v175, 0, v60, v51
	s_add_i32 s0, s58, -1
	v_add3_u32 v178, 0, v48, v3
	v_add3_u32 v179, 0, v3, v48
	v_mov_b32_e32 v164, v158
	v_mov_b32_e32 v165, v158
	v_mov_b32_e32 v161, v160
	v_mov_b32_e32 v166, v160
	v_mov_b32_e32 v167, v160
	v_mov_b32_e32 v163, v162
	v_mov_b32_e32 v168, v162
	v_mov_b32_e32 v169, v162
	v_lshl_add_u64 v[170:171], v[0:1], 0, v[48:49]
	v_xad_u32 v180, v173, -1, s55
	v_lshlrev_b32_e32 v181, 1, v50
	v_readlane_b32 s77, v254, 1
	v_readlane_b32 s80, v254, 4
	v_readlane_b32 s81, v254, 5
	v_readlane_b32 s82, v254, 6
	v_readlane_b32 s83, v254, 7
	s_and_b32 s98, vcc_lo, 32
	s_sub_i32 s98, s98, 16
	s_lshl_b32 s99, s98, 1
	s_add_i32 s101, s99, s98
	s_ashr_i32 s100, s98, 4
	v_xad_u32 v187, v174, -1, s55
	v_cndmask_b32_e32 v187, v187, v174, vcc
	v_add_u32_e32 v187, s56, v187
	s_waitcnt vmcnt(0)
.LBB0_1370:
	s_add_i32 s1, s57, -1
	s_waitcnt vmcnt(7)
	ds_write_b128 v175, v[72:75]
	ds_write_b128 v175, v[68:71] offset:8704
	ds_write_b128 v175, v[64:67] offset:17408
	v_cndmask_b32_e32 v65, v180, v173, vcc
	s_min_u32 s18, s1, s0
	v_add_u32_e32 v66, s56, v65
	s_lshl_b32 s18, s18, 5
	s_mul_i32 s18, s18, s100
	v_ashrrev_i32_e32 v67, 31, v66
	v_add_u32_e32 v236, s98, v66
	v_add_u32_e32 v238, s99, v66
	v_add_u32_e32 v240, s101, v66
	v_lshlrev_b64 v[64:65], 11, v[66:67]
	v_lshl_add_u64 v[242:243], v[170:171], 0, v[64:65]
	s_min_u32 s42, s57, s0
	v_add_u32_e32 v64, s18, v187
	s_lshl_b32 s42, s42, 5
	s_mul_i32 s42, s42, s100
	v_cvt_pk_bf16_f32 v60, v44, v45
	v_cvt_pk_bf16_f32 v61, v46, v47
	v_cvt_pk_bf16_f32 v62, v40, v41
	v_cvt_pk_bf16_f32 v63, v42, v43
	v_lshl_or_b32 v64, v64, 13, v181
	v_add_u32_e32 v244, s42, v187
	global_load_dwordx4 v[72:75], v64, s[36:37]
	s_nop 0
	global_load_dwordx4 v[68:71], v64, s[38:39]
	s_nop 0
	global_load_dwordx4 v[64:67], v64, s[40:41]
	s_waitcnt lgkmcnt(0)
	s_barrier
	ds_read_b64 v[188:189], v178
	ds_read_b64 v[190:191], v178 offset:32
	ds_read_b64 v[192:193], v178 offset:4352
	ds_read_b64 v[194:195], v178 offset:4384
	ds_read_b64 v[196:197], v178 offset:4416
	ds_read_b64 v[198:199], v178 offset:4448
	ds_read_b64 v[200:201], v179 offset:8704
	ds_read_b64 v[202:203], v179 offset:8736
	ds_read_b64 v[204:205], v179 offset:13056
	ds_read_b64 v[206:207], v179 offset:13088
	ds_read_b64_tr_b16 v[210:211], v176 offset:13056
	ds_read_b64_tr_b16 v[212:213], v177 offset:17408
	ds_read_b64_tr_b16 v[214:215], v177 offset:21760
	ds_read_b64_tr_b16 v[208:209], v176 offset:8704
	ds_read_b64_tr_b16 v[216:217], v176 offset:8736
	ds_read_b64_tr_b16 v[220:221], v176 offset:8768
	ds_read_b64_tr_b16 v[222:223], v176 offset:13120
	ds_read_b64_tr_b16 v[218:219], v176 offset:13088
	ds_read_b64_tr_b16 v[230:231], v176 offset:8928
	s_waitcnt lgkmcnt(7)
	v_lshlrev_b32_e32 v232, 16, v212
	v_and_b32_e32 v233, 0xffff0000, v212
	v_lshlrev_b32_e32 v234, 16, v213
	v_and_b32_e32 v235, 0xffff0000, v213
	s_waitcnt lgkmcnt(6)
	v_lshlrev_b32_e32 v246, 16, v214
	v_and_b32_e32 v247, 0xffff0000, v214
	v_lshlrev_b32_e32 v248, 16, v215
	v_and_b32_e32 v249, 0xffff0000, v215
	v_mov_b32_e32 v159, v158
	v_mfma_f32_16x16x32_bf16 v[226:229], v[60:63], v[192:195], 0
	v_mul_f32_e64 v232, v150, v232
	v_mul_f32_e64 v233, v151, v233
	v_pk_mul_f32 v[234:235], v[152:153], v[234:235]
	v_pk_mul_f32 v[44:45], v[164:165], v[44:45]
	v_mfma_f32_16x16x32_bf16 v[60:63], v[60:63], v[188:191], 0
	v_mul_f32_e64 v46, v158, v46
	v_mul_f32_e64 v47, v159, v47
	v_pk_mul_f32 v[40:41], v[164:165], v[40:41]
	v_pk_mul_f32 v[42:43], v[158:159], v[42:43]
	v_mfma_f32_16x16x32_bf16 v[188:191], v[200:203], v[188:191], 0
	v_cvt_pk_bf16_f32 v52, v36, v37
	v_cvt_pk_bf16_f32 v53, v38, v39
	v_cvt_pk_bf16_f32 v54, v32, v33
	v_mfma_f32_16x16x32_bf16 v[200:203], v[200:203], v[192:195], 0
	v_cvt_pk_bf16_f32 v55, v34, v35
	v_cvt_pk_bf16_f32 v56, v28, v29
	v_cvt_pk_bf16_f32 v57, v30, v31
	v_mfma_f32_16x16x32_bf16 v[192:195], v[204:207], v[192:195], 0
	v_mul_f32_e64 v206, v154, v246
	v_mul_f32_e64 v207, v155, v247
	v_pk_mul_f32 v[246:247], v[156:157], v[248:249]
	v_cvt_pk_bf16_f32 v204, v232, v233
	v_cvt_pk_bf16_f32 v205, v234, v235
	v_cvt_pk_bf16_f32 v206, v206, v207
	v_cvt_pk_bf16_f32 v207, v246, v247
	v_pk_mul_f32 v[36:37], v[164:165], v[36:37]
	v_pk_mul_f32 v[32:33], v[164:165], v[32:33]
	s_waitcnt lgkmcnt(5)
	v_mfma_f32_16x16x32_bf16 v[44:47], v[208:211], v[204:207], v[44:47]
	ds_read_b64_tr_b16 v[210:211], v176 offset:13152
	ds_read_b64_tr_b16 v[208:209], v176 offset:8800
	ds_read_b64_tr_b16 v[232:233], v176 offset:8832
	v_pk_mul_f32 v[28:29], v[164:165], v[28:29]
	v_pk_mul_f32 v[38:39], v[158:159], v[38:39]
	s_waitcnt lgkmcnt(4)
	v_mfma_f32_16x16x32_bf16 v[40:43], v[216:219], v[204:207], v[40:43]
	ds_read_b64_tr_b16 v[216:217], v176 offset:8864
	ds_read_b64_tr_b16 v[234:235], v176 offset:13184
	ds_read_b64_tr_b16 v[218:219], v176 offset:13216
	v_pk_mul_f32 v[34:35], v[158:159], v[34:35]
	v_pk_mul_f32 v[30:31], v[158:159], v[30:31]
	v_mfma_f32_16x16x32_bf16 v[36:39], v[220:223], v[204:207], v[36:39]
	v_ashrrev_i32_e32 v237, 31, v236
	v_cvt_pk_bf16_f32 v58, v24, v25
	s_waitcnt lgkmcnt(4)
	v_mfma_f32_16x16x32_bf16 v[32:35], v[208:211], v[204:207], v[32:35]
	ds_read_b64_tr_b16 v[208:209], v176 offset:8896
	ds_read_b64_tr_b16 v[210:211], v176 offset:13248
	v_cvt_pk_bf16_f32 v59, v26, v27
	s_waitcnt lgkmcnt(3)
	v_mfma_f32_16x16x32_bf16 v[220:223], v[232:235], v[204:207], v[28:31]
	ds_read_b64_tr_b16 v[232:233], v176 offset:13280
	v_cvt_pk_bf16_f32 v48, v20, v21
	v_cvt_pk_bf16_f32 v49, v22, v23
	v_lshl_or_b32 v244, v244, 13, v181
	v_cvt_pk_bf16_f32 v50, v16, v17
	v_cvt_pk_bf16_f32 v51, v18, v19
	v_pk_mul_f32 v[24:25], v[164:165], v[24:25]
	v_pk_mul_f32 v[20:21], v[164:165], v[20:21]
	v_pk_mul_f32 v[16:17], v[164:165], v[16:17]
	v_pk_mul_f32 v[26:27], v[158:159], v[26:27]
	v_pk_mul_f32 v[22:23], v[158:159], v[22:23]
	v_pk_mul_f32 v[18:19], v[158:159], v[18:19]
	v_ashrrev_i32_e32 v239, 31, v238
	v_ashrrev_i32_e32 v241, 31, v240
	v_lshlrev_b64 v[236:237], 11, v[236:237]
	v_lshlrev_b64 v[246:247], 11, v[238:239]
	v_lshlrev_b64 v[248:249], 11, v[240:241]
	s_waitcnt lgkmcnt(3)
	v_mfma_f32_16x16x32_bf16 v[216:219], v[216:219], v[204:207], v[24:27]
	v_lshl_add_u64 v[234:235], v[170:171], 0, v[236:237]
	s_waitcnt lgkmcnt(1)
	v_mfma_f32_16x16x32_bf16 v[208:211], v[208:211], v[204:207], v[20:23]
	ds_read_b64 v[24:25], v179 offset:8768
	ds_read_b64 v[26:27], v179 offset:8800
	ds_read_b64 v[28:29], v179 offset:13120
	ds_read_b64 v[30:31], v179 offset:13152
	s_waitcnt lgkmcnt(4)
	v_mfma_f32_16x16x32_bf16 v[204:207], v[230:233], v[204:207], v[16:19]
	v_mov_b32_e32 v3, v2
	ds_read_b64 v[16:17], v178 offset:64
	ds_read_b64 v[18:19], v178 offset:96
	v_mfma_f32_16x16x32_bf16 v[226:229], v[52:55], v[196:199], v[226:229]
	v_add_u32_e32 v186, 0x9800, v179
	s_add_i32 s57, s57, 2
	s_waitcnt lgkmcnt(0)
	v_mfma_f32_16x16x32_bf16 v[20:23], v[52:55], v[16:19], v[60:63]
	ds_read_b64 v[52:53], v178 offset:4480
	ds_read_b64 v[54:55], v178 offset:4512
	s_nop 1
	ds_read_b64 v[60:61], v178 offset:128
	ds_read_b64 v[62:63], v178 offset:160
	v_add_u32_e32 v173, 64, v173
	v_subrev_u32_e32 v180, 64, v180
	v_mfma_f32_16x16x32_bf16 v[16:19], v[24:27], v[16:19], v[188:191]
	s_cmp_ge_u32 s1, s58
	v_mfma_f32_16x16x32_bf16 v[24:27], v[24:27], v[196:199], v[200:203]
	v_mfma_f32_16x16x32_bf16 v[28:31], v[28:31], v[196:199], v[192:195]
	s_nop 2
	ds_read_b64 v[192:193], v179 offset:8832
	ds_read_b64 v[194:195], v179 offset:8864
	ds_read_b64 v[196:197], v178 offset:192
	ds_read_b64 v[198:199], v178 offset:224
	ds_read_b64 v[200:201], v178 offset:4544
	ds_read_b64 v[202:203], v178 offset:4576
	s_waitcnt lgkmcnt(8)
	v_mfma_f32_16x16x32_bf16 v[188:191], v[56:59], v[52:55], v[226:229]
	s_waitcnt lgkmcnt(6)
	v_mfma_f32_16x16x32_bf16 v[20:23], v[56:59], v[60:63], v[20:23]
	ds_read_b64 v[56:57], v179 offset:13184
	ds_read_b64 v[58:59], v179 offset:13216
	ds_read_b64 v[226:227], v179 offset:8896
	ds_read_b64 v[228:229], v179 offset:8928
	ds_read_b64 v[230:231], v179 offset:13248
	ds_read_b64 v[232:233], v179 offset:13280
	s_waitcnt vmcnt(5)
	ds_write_b128 v175, v[12:15] offset:26112
	ds_write_b128 v175, v[8:11] offset:34816
	ds_write_b128 v175, v[4:7] offset:43520
	s_waitcnt lgkmcnt(13)
	v_mfma_f32_16x16x32_bf16 v[16:19], v[192:195], v[60:63], v[16:19]
	v_mfma_f32_16x16x32_bf16 v[4:7], v[192:195], v[52:55], v[24:27]
	s_waitcnt lgkmcnt(7)
	v_mfma_f32_16x16x32_bf16 v[8:11], v[56:59], v[52:55], v[28:31]
	s_nop 0
	v_cvt_pk_bf16_f32 v24, v44, v45
	v_cvt_pk_bf16_f32 v25, v46, v47
	v_cvt_pk_bf16_f32 v26, v40, v41
	s_waitcnt lgkmcnt(5)
	v_mfma_f32_16x16x32_bf16 v[16:19], v[226:229], v[196:199], v[16:19]
	v_mul_f32_e64 v28, v164, v44
	v_mul_f32_e64 v29, v165, v45
	v_cvt_pk_bf16_f32 v27, v42, v43
	v_pk_mul_f32 v[30:31], v[158:159], v[46:47]
	v_mfma_f32_16x16x32_bf16 v[4:7], v[226:229], v[200:203], v[4:7]
	v_cvt_pk_bf16_f32 v52, v36, v37
	s_nop 1
	v_pk_mul_f32 v[18:19], v[146:147], v[18:19]
	v_pk_mul_f32 v[0:1], v[142:143], v[16:17]
	s_waitcnt lgkmcnt(3)
	v_mfma_f32_16x16x32_bf16 v[8:11], v[230:233], v[200:203], v[8:11]
	v_cvt_pk_bf16_f32 v0, v0, v1
	v_pk_mul_f32 v[6:7], v[148:149], v[6:7]
	v_pk_mul_f32 v[4:5], v[144:145], v[4:5]
	v_cvt_pk_bf16_f32 v1, v18, v19
	v_cvt_pk_bf16_f32 v4, v4, v5
	s_nop 2
	v_pk_mul_f32 v[16:17], v[146:147], v[10:11]
	v_pk_mul_f32 v[44:45], v[142:143], v[8:9]
	v_cvt_pk_bf16_f32 v5, v6, v7
	v_cvt_pk_bf16_f32 v6, v44, v45
	v_cvt_pk_bf16_f32 v7, v16, v17
	v_mfma_f32_16x16x32_bf16 v[12:15], v[48:51], v[200:203], v[188:191]
	v_cvt_pk_bf16_f32 v53, v38, v39
	v_pk_mul_f32 v[38:39], v[158:159], v[38:39]
	v_pk_mul_f32 v[36:37], v[164:165], v[36:37]
	v_mfma_f32_16x16x32_bf16 v[20:23], v[48:51], v[196:199], v[20:23]
	v_cvt_pk_bf16_f32 v54, v32, v33
	v_cvt_pk_bf16_f32 v55, v34, v35
	v_pk_mul_f32 v[42:43], v[158:159], v[42:43]
	v_mfma_f32_16x16x32_bf16 v[8:11], v[212:215], v[0:3], 0
	v_mul_f32_e64 v40, v164, v40
	v_mul_f32_e64 v41, v165, v41
	v_pk_mul_f32 v[34:35], v[158:159], v[34:35]
	v_pk_mul_f32 v[32:33], v[164:165], v[32:33]
	v_mfma_f32_16x16x32_bf16 v[4:7], v[212:215], v[4:7], 0
	v_mul_f32_e64 v50, v158, v222
	v_mul_f32_e64 v51, v159, v223
	s_nop 0
	v_pk_fma_f32 v[8:9], v[162:163], v[20:21], v[8:9]
	v_pk_mul_f32 v[48:49], v[164:165], v[220:221]
	v_cvt_pk_bf16_f32 v8, v8, v9
	v_cvt_pk_bf16_f32 v56, v220, v221
	s_nop 0
	v_pk_fma_f32 v[0:1], v[166:167], v[14:15], v[6:7]
	v_pk_fma_f32 v[6:7], v[168:169], v[22:23], v[10:11]
	v_pk_fma_f32 v[4:5], v[160:161], v[12:13], v[4:5]
	v_cvt_pk_bf16_f32 v9, v6, v7
	v_cvt_pk_bf16_f32 v4, v4, v5
	v_cvt_pk_bf16_f32 v5, v0, v1
	global_store_dwordx2 v[242:243], v[8:9], off
	global_store_dwordx2 v[234:235], v[4:5], off
	global_load_dwordx4 v[12:15], v244, s[36:37]
	s_nop 0
	global_load_dwordx4 v[8:11], v244, s[38:39]
	global_load_dwordx4 v[4:7], v244, s[40:41]
	s_waitcnt lgkmcnt(0)
	s_barrier
	ds_read_b64 v[16:17], v178 offset:26112
	ds_read_b64 v[18:19], v178 offset:26144
	ds_read_b64 v[20:21], v178 offset:30464
	ds_read_b64 v[22:23], v178 offset:30496
	ds_read_b64 v[60:61], v178 offset:30528
	ds_read_b64 v[62:63], v178 offset:30560
	ds_read_b64 v[44:45], v179 offset:34816
	ds_read_b64 v[46:47], v179 offset:34848
	ds_read_b64 v[188:189], v186 offset:256
	ds_read_b64 v[190:191], v186 offset:288
	ds_read_b64_tr_b16 v[194:195], v176 offset:39168
	ds_read_b64_tr_b16 v[196:197], v177 offset:43520
	ds_read_b64_tr_b16 v[198:199], v177 offset:47872
	ds_read_b64_tr_b16 v[192:193], v176 offset:34816
	ds_read_b64_tr_b16 v[200:201], v176 offset:34848
	ds_read_b64_tr_b16 v[212:213], v176 offset:34880
	ds_read_b64_tr_b16 v[214:215], v176 offset:39232
	s_waitcnt lgkmcnt(13)
	v_mfma_f32_16x16x32_bf16 v[226:229], v[24:27], v[20:23], 0
	s_waitcnt lgkmcnt(5)
	v_lshlrev_b32_e32 v0, 16, v196
	v_and_b32_e32 v1, 0xffff0000, v196
	v_pk_mul_f32 v[0:1], v[150:151], v[0:1]
	v_mfma_f32_16x16x32_bf16 v[234:237], v[24:27], v[16:19], 0
	v_lshlrev_b32_e32 v24, 16, v197
	v_and_b32_e32 v25, 0xffff0000, v197
	v_pk_mul_f32 v[24:25], v[152:153], v[24:25]
	v_mfma_f32_16x16x32_bf16 v[238:241], v[44:47], v[16:19], 0
	s_waitcnt lgkmcnt(4)
	v_lshlrev_b32_e32 v16, 16, v198
	v_and_b32_e32 v17, 0xffff0000, v198
	v_lshlrev_b32_e32 v18, 16, v199
	v_and_b32_e32 v19, 0xffff0000, v199
	v_mfma_f32_16x16x32_bf16 v[242:245], v[44:47], v[20:23], 0
	ds_read_b64_tr_b16 v[202:203], v176 offset:39200
	ds_read_b64_tr_b16 v[230:231], v176 offset:35040
	v_cvt_pk_bf16_f32 v57, v222, v223
	v_cvt_pk_bf16_f32 v58, v216, v217
	v_mfma_f32_16x16x32_bf16 v[188:191], v[188:191], v[20:23], 0
	v_mul_f32_e64 v20, v154, v16
	v_mul_f32_e64 v21, v155, v17
	v_pk_mul_f32 v[22:23], v[156:157], v[18:19]
	v_cvt_pk_bf16_f32 v16, v0, v1
	v_cvt_pk_bf16_f32 v17, v24, v25
	v_cvt_pk_bf16_f32 v18, v20, v21
	v_cvt_pk_bf16_f32 v19, v22, v23
	ds_read_b64_tr_b16 v[22:23], v176 offset:39264
	ds_read_b64_tr_b16 v[20:21], v176 offset:34912
	ds_read_b64_tr_b16 v[24:25], v176 offset:34944
	s_waitcnt lgkmcnt(8)
	v_mfma_f32_16x16x32_bf16 v[44:47], v[192:195], v[16:19], v[28:31]
	ds_read_b64_tr_b16 v[192:193], v176 offset:34976
	ds_read_b64_tr_b16 v[26:27], v176 offset:39296
	ds_read_b64_tr_b16 v[194:195], v176 offset:39328
	ds_read_b64_tr_b16 v[232:233], v176 offset:39392
	v_cvt_pk_bf16_f32 v59, v218, v219
	s_waitcnt lgkmcnt(9)
	v_mfma_f32_16x16x32_bf16 v[36:39], v[212:215], v[16:19], v[36:39]
	ds_read_b64_tr_b16 v[212:213], v176 offset:35008
	ds_read_b64_tr_b16 v[214:215], v176 offset:39360
	s_waitcnt lgkmcnt(10)
	v_mfma_f32_16x16x32_bf16 v[40:43], v[200:203], v[16:19], v[40:43]
	v_mul_f32_e64 v202, v158, v218
	v_mul_f32_e64 v203, v159, v219
	v_pk_mul_f32 v[200:201], v[164:165], v[216:217]
	ds_read_b64 v[216:217], v178 offset:26240
	ds_read_b64 v[218:219], v178 offset:26272
	s_waitcnt lgkmcnt(9)
	v_mfma_f32_16x16x32_bf16 v[32:35], v[20:23], v[16:19], v[32:35]
	v_mul_f32_e64 v22, v158, v210
	v_mul_f32_e64 v23, v159, v211
	v_pk_mul_f32 v[20:21], v[164:165], v[208:209]
	s_waitcnt lgkmcnt(6)
	v_mfma_f32_16x16x32_bf16 v[28:31], v[24:27], v[16:19], v[48:51]
	s_waitcnt lgkmcnt(5)
	v_mfma_f32_16x16x32_bf16 v[24:27], v[192:195], v[16:19], v[200:203]
	ds_read_b64 v[192:193], v179 offset:34880
	ds_read_b64 v[194:195], v179 offset:34912
	v_pk_mul_f32 v[50:51], v[158:159], v[206:207]
	v_pk_mul_f32 v[48:49], v[164:165], v[204:205]
	s_waitcnt lgkmcnt(4)
	v_mfma_f32_16x16x32_bf16 v[20:23], v[212:215], v[16:19], v[20:23]
	ds_read_b64 v[212:213], v186 offset:320
	ds_read_b64 v[214:215], v186 offset:352
	v_cvt_pk_bf16_f32 v202, v204, v205
	v_cvt_pk_bf16_f32 v203, v206, v207
	v_mfma_f32_16x16x32_bf16 v[16:19], v[230:233], v[16:19], v[48:51]
	ds_read_b64 v[204:205], v178 offset:26304
	ds_read_b64 v[206:207], v178 offset:26336
	v_cvt_pk_bf16_f32 v200, v208, v209
	v_cvt_pk_bf16_f32 v201, v210, v211
	ds_read_b64 v[48:49], v178 offset:26176
	ds_read_b64 v[50:51], v178 offset:26208
	v_mfma_f32_16x16x32_bf16 v[226:229], v[52:55], v[60:63], v[226:229]
	s_waitcnt lgkmcnt(0)
	v_mfma_f32_16x16x32_bf16 v[52:55], v[52:55], v[48:51], v[234:237]
	v_mfma_f32_16x16x32_bf16 v[48:51], v[192:195], v[48:51], v[238:241]
	v_mfma_f32_16x16x32_bf16 v[192:195], v[192:195], v[60:63], v[242:245]
	v_mfma_f32_16x16x32_bf16 v[60:63], v[212:215], v[60:63], v[188:191]
	s_nop 2
	ds_read_b64 v[188:189], v178 offset:30592
	ds_read_b64 v[190:191], v178 offset:30624
	s_waitcnt lgkmcnt(0)
	v_mfma_f32_16x16x32_bf16 v[212:215], v[56:59], v[188:191], v[226:229]
	v_mfma_f32_16x16x32_bf16 v[52:55], v[56:59], v[216:219], v[52:55]
	ds_read_b64 v[56:57], v179 offset:34944
	ds_read_b64 v[58:59], v179 offset:34976
	s_waitcnt lgkmcnt(0)
	v_mfma_f32_16x16x32_bf16 v[48:51], v[56:59], v[216:219], v[48:51]
	v_mfma_f32_16x16x32_bf16 v[56:59], v[56:59], v[188:191], v[192:195]
	s_nop 2
	ds_read_b64 v[192:193], v186 offset:384
	ds_read_b64 v[194:195], v186 offset:416
	s_waitcnt lgkmcnt(0)
	v_mfma_f32_16x16x32_bf16 v[60:63], v[192:195], v[188:191], v[60:63]
	ds_read_b64 v[188:189], v178 offset:30656
	ds_read_b64 v[190:191], v178 offset:30688
	ds_read_b64 v[182:183], v179 offset:35008
	ds_read_b64 v[184:185], v179 offset:35040
	s_waitcnt lgkmcnt(0)
	v_mfma_f32_16x16x32_bf16 v[48:51], v[182:185], v[204:207], v[48:51]
	s_nop 7
	v_pk_mul_f32 v[50:51], v[146:147], v[50:51]
	v_mfma_f32_16x16x32_bf16 v[56:59], v[182:185], v[188:191], v[56:59]
	ds_read_b64 v[182:183], v186 offset:448
	ds_read_b64 v[184:185], v186 offset:480
	v_pk_mul_f32 v[0:1], v[142:143], v[48:49]
	s_waitcnt lgkmcnt(0)
	v_mfma_f32_16x16x32_bf16 v[60:63], v[182:185], v[188:191], v[60:63]
	s_nop 3
	v_mul_f32_e64 v182, v148, v58
	v_mul_f32_e64 v183, v149, v59
	v_pk_mul_f32 v[48:49], v[144:145], v[56:57]
	v_cvt_pk_bf16_f32 v0, v0, v1
	v_pk_mul_f32 v[62:63], v[146:147], v[62:63]
	v_pk_mul_f32 v[60:61], v[142:143], v[60:61]
	v_cvt_pk_bf16_f32 v1, v50, v51
	v_cvt_pk_bf16_f32 v48, v48, v49
	v_cvt_pk_bf16_f32 v49, v182, v183
	v_cvt_pk_bf16_f32 v50, v60, v61
	v_cvt_pk_bf16_f32 v51, v62, v63
	v_mfma_f32_16x16x32_bf16 v[192:195], v[200:203], v[188:191], v[212:215]
	v_mfma_f32_16x16x32_bf16 v[52:55], v[200:203], v[204:207], v[52:55]
	v_lshl_add_u64 v[200:201], v[170:171], 0, v[246:247]
	v_lshl_add_u64 v[202:203], v[170:171], 0, v[248:249]
	v_mfma_f32_16x16x32_bf16 v[56:59], v[196:199], v[0:3], 0
	v_mfma_f32_16x16x32_bf16 v[48:51], v[196:199], v[48:51], 0
	s_nop 6
	v_fma_f32 v52, v162, v52, v56
	v_fma_f32 v53, v163, v53, v57
	v_pk_fma_f32 v[0:1], v[166:167], v[194:195], v[50:51]
	v_pk_fma_f32 v[50:51], v[168:169], v[54:55], v[58:59]
	v_pk_fma_f32 v[48:49], v[160:161], v[192:193], v[48:49]
	v_cvt_pk_bf16_f32 v52, v52, v53
	v_cvt_pk_bf16_f32 v53, v50, v51
	v_cvt_pk_bf16_f32 v48, v48, v49
	v_cvt_pk_bf16_f32 v49, v0, v1
	global_store_dwordx2 v[200:201], v[52:53], off
	global_store_dwordx2 v[202:203], v[48:49], off
	s_cbranch_scc0 .LBB0_1370
	s_andn2_b64 vcc, exec, s[6:7]
	s_cbranch_vccnz .LBB0_1354
	s_add_u32 s0, s28, s14
	s_addc_u32 s1, s29, s15
	v_lshl_add_u64 v[0:1], v[112:113], 2, s[0:1]
	s_waitcnt vmcnt(2)
	v_lshl_add_u64 v[4:5], v[0:1], 0, v[76:77]
	global_store_dword v[4:5], v44, off nt
	v_lshl_add_u64 v[4:5], v[0:1], 0, v[78:79]
	global_store_dword v[4:5], v45, off nt
	v_lshl_add_u64 v[4:5], v[0:1], 0, v[80:81]
	global_store_dword v[4:5], v46, off nt
	v_lshl_add_u64 v[4:5], v[0:1], 0, v[82:83]
	global_store_dword v[4:5], v47, off nt
	v_lshl_add_u64 v[4:5], v[0:1], 0, v[84:85]
	global_store_dword v[4:5], v40, off nt
	v_lshl_add_u64 v[4:5], v[0:1], 0, v[86:87]
	global_store_dword v[4:5], v41, off nt
	v_lshl_add_u64 v[4:5], v[0:1], 0, v[88:89]
	global_store_dword v[4:5], v42, off nt
	v_lshl_add_u64 v[4:5], v[0:1], 0, v[90:91]
	global_store_dword v[4:5], v43, off nt
	v_lshl_add_u64 v[4:5], v[0:1], 0, v[92:93]
	global_store_dword v[4:5], v36, off nt
	v_lshl_add_u64 v[4:5], v[0:1], 0, v[94:95]
	global_store_dword v[4:5], v37, off nt
	v_lshl_add_u64 v[4:5], v[0:1], 0, v[96:97]
	global_store_dword v[4:5], v38, off nt
	v_lshl_add_u64 v[4:5], v[0:1], 0, v[98:99]
	global_store_dword v[4:5], v39, off nt
	v_lshl_add_u64 v[4:5], v[0:1], 0, v[100:101]
	global_store_dword v[4:5], v32, off nt
	v_lshl_add_u64 v[4:5], v[0:1], 0, v[102:103]
	global_store_dword v[4:5], v33, off nt
	v_lshl_add_u64 v[4:5], v[0:1], 0, v[104:105]
	global_store_dword v[4:5], v34, off nt
	v_lshl_add_u64 v[4:5], v[0:1], 0, v[106:107]
	global_store_dword v[4:5], v35, off nt
	v_lshl_add_u64 v[4:5], v[0:1], 0, v[108:109]
	global_store_dword v[4:5], v28, off nt
	v_lshl_add_u64 v[4:5], v[0:1], 0, v[110:111]
	global_store_dword v[4:5], v29, off nt
	v_lshl_add_u64 v[4:5], v[0:1], 0, v[138:139]
	global_store_dword v[4:5], v30, off nt
	v_lshl_add_u64 v[4:5], v[0:1], 0, v[136:137]
	global_store_dword v[4:5], v31, off nt
	v_lshl_add_u64 v[4:5], v[0:1], 0, v[134:135]
	global_store_dword v[4:5], v24, off nt
	v_lshl_add_u64 v[4:5], v[0:1], 0, v[132:133]
	global_store_dword v[4:5], v25, off nt
	v_lshl_add_u64 v[4:5], v[0:1], 0, v[130:131]
	global_store_dword v[4:5], v26, off nt
	v_lshl_add_u64 v[4:5], v[0:1], 0, v[128:129]
	global_store_dword v[4:5], v27, off nt
	v_lshl_add_u64 v[4:5], v[0:1], 0, v[126:127]
	global_store_dword v[4:5], v20, off nt
	v_lshl_add_u64 v[4:5], v[0:1], 0, v[124:125]
	global_store_dword v[4:5], v21, off nt
	v_lshl_add_u64 v[4:5], v[0:1], 0, v[122:123]
	global_store_dword v[4:5], v22, off nt
	v_lshl_add_u64 v[4:5], v[0:1], 0, v[120:121]
	global_store_dword v[4:5], v23, off nt
	v_lshl_add_u64 v[4:5], v[0:1], 0, v[118:119]
	global_store_dword v[4:5], v16, off nt
	v_lshl_add_u64 v[4:5], v[0:1], 0, v[116:117]
	global_store_dword v[4:5], v17, off nt
	v_lshl_add_u64 v[4:5], v[0:1], 0, v[114:115]
	v_lshl_add_u64 v[0:1], v[0:1], 0, v[140:141]
	global_store_dword v[4:5], v18, off nt
	global_store_dword v[0:1], v19, off nt
	s_branch .LBB0_1354
